# MFMA order: operand snake with k outer (every transition shares srcA or srcB, same-accumulator distance 5..12)
# baseline (speedup 1.0000x reference)
.LBB0_32:
	s_add_u32 s28, s54, 0xfff80080
	s_addc_u32 s29, s55, -1
	s_add_i32 s30, 0, 0x10000
	s_cmp_eq_u32 s27, 28
	s_cselect_b32 s79, s13, s29
	s_cselect_b32 s78, s16, s28
	s_cselect_b32 s69, s9, s26
	s_cselect_b32 s68, s24, s25
	s_add_i32 s31, 0, 0x14000
	v_add_u32_e32 v142, s30, v184
	v_add_u32_e32 v172, s31, v184
	ds_read_b128 v[130:133], v142
	ds_read_b128 v[134:137], v142 offset:1024
	ds_read_b128 v[138:141], v142 offset:2048
	ds_read_b128 v[142:145], v142 offset:3072
	ds_read_b128 v[146:149], v172
	ds_read_b128 v[150:153], v172 offset:1024
	ds_read_b128 v[154:157], v172 offset:2048
	ds_read_b128 v[172:175], v172 offset:3072
	v_lshl_add_u64 v[212:213], s[54:55], 0, v[166:167]
	s_add_i32 m0, s42, 0xc000
	ds_read_b128 v[176:179], v186
	ds_read_b128 v[180:183], v186 offset:1024
	ds_read_b128 v[188:191], v186 offset:2048
	ds_read_b128 v[192:195], v186 offset:3072
	ds_read_b128 v[196:199], v186 offset:4096
	ds_read_b128 v[200:203], v186 offset:5120
	ds_read_b128 v[204:207], v186 offset:6144
	ds_read_b128 v[208:211], v186 offset:7168
	global_load_lds_dwordx4 v[212:213], off
	v_lshl_add_u64 v[212:213], s[54:55], 0, v[168:169]
	s_add_i32 m0, s42, 0xe000
	s_nop 0
	global_load_lds_dwordx4 v[212:213], off
	s_waitcnt vmcnt(8)
	s_waitcnt lgkmcnt(0)
	s_barrier
	s_setprio 1
	s_waitcnt lgkmcnt(0)
	v_mfma_f32_16x16x32_bf16 v[126:129], v[130:133], v[176:179], v[126:129]
	v_mfma_f32_16x16x32_bf16 v[110:113], v[130:133], v[188:191], v[110:113]
	v_mfma_f32_16x16x32_bf16 v[94:97], v[130:133], v[196:199], v[94:97]
	v_mfma_f32_16x16x32_bf16 v[78:81], v[130:133], v[204:207], v[78:81]
	v_mfma_f32_16x16x32_bf16 v[74:77], v[138:141], v[204:207], v[74:77]
	v_mfma_f32_16x16x32_bf16 v[90:93], v[138:141], v[196:199], v[90:93]
	v_mfma_f32_16x16x32_bf16 v[106:109], v[138:141], v[188:191], v[106:109]
	v_mfma_f32_16x16x32_bf16 v[122:125], v[138:141], v[176:179], v[122:125]
	v_mfma_f32_16x16x32_bf16 v[122:125], v[142:145], v[180:183], v[122:125]
	v_mfma_f32_16x16x32_bf16 v[106:109], v[142:145], v[192:195], v[106:109]
	v_mfma_f32_16x16x32_bf16 v[90:93], v[142:145], v[200:203], v[90:93]
	v_mfma_f32_16x16x32_bf16 v[74:77], v[142:145], v[208:211], v[74:77]
	v_mfma_f32_16x16x32_bf16 v[78:81], v[134:137], v[208:211], v[78:81]
	v_mfma_f32_16x16x32_bf16 v[94:97], v[134:137], v[200:203], v[94:97]
	v_mfma_f32_16x16x32_bf16 v[110:113], v[134:137], v[192:195], v[110:113]
	v_mfma_f32_16x16x32_bf16 v[126:129], v[134:137], v[180:183], v[126:129]
	s_setprio 0
	s_setprio 1
	v_mfma_f32_16x16x32_bf16 v[118:121], v[146:149], v[176:179], v[118:121]
	v_mfma_f32_16x16x32_bf16 v[102:105], v[146:149], v[188:191], v[102:105]
	v_mfma_f32_16x16x32_bf16 v[86:89], v[146:149], v[196:199], v[86:89]
	v_mfma_f32_16x16x32_bf16 v[70:73], v[146:149], v[204:207], v[70:73]
	v_mfma_f32_16x16x32_bf16 v[66:69], v[154:157], v[204:207], v[66:69]
	v_mfma_f32_16x16x32_bf16 v[82:85], v[154:157], v[196:199], v[82:85]
	v_mfma_f32_16x16x32_bf16 v[98:101], v[154:157], v[188:191], v[98:101]
	v_mfma_f32_16x16x32_bf16 v[114:117], v[154:157], v[176:179], v[114:117]
	v_mfma_f32_16x16x32_bf16 v[114:117], v[172:175], v[180:183], v[114:117]
	v_mfma_f32_16x16x32_bf16 v[98:101], v[172:175], v[192:195], v[98:101]
	v_mfma_f32_16x16x32_bf16 v[82:85], v[172:175], v[200:203], v[82:85]
	v_mfma_f32_16x16x32_bf16 v[66:69], v[172:175], v[208:211], v[66:69]
	v_mfma_f32_16x16x32_bf16 v[70:73], v[150:153], v[208:211], v[70:73]
	v_mfma_f32_16x16x32_bf16 v[86:89], v[150:153], v[200:203], v[86:89]
	v_mfma_f32_16x16x32_bf16 v[102:105], v[150:153], v[192:195], v[102:105]
	v_mfma_f32_16x16x32_bf16 v[118:121], v[150:153], v[180:183], v[118:121]
	s_setprio 0
	s_barrier
	s_add_i32 s28, s30, s11
	v_lshl_add_u64 v[212:213], s[68:69], 0, v[160:161]
	s_mov_b32 m0, s28
	ds_read_b128 v[176:179], v186 offset:16384
	ds_read_b128 v[180:183], v186 offset:17408
	ds_read_b128 v[188:191], v186 offset:18432
	ds_read_b128 v[192:195], v186 offset:19456
	ds_read_b128 v[196:199], v186 offset:20480
	ds_read_b128 v[200:203], v186 offset:21504
	ds_read_b128 v[204:207], v186 offset:22528
	ds_read_b128 v[208:211], v186 offset:23552
	global_load_lds_dwordx4 v[212:213], off
	s_add_i32 m0, s28, 0x2000
	s_add_u32 s28, s68, 0x80000
	v_lshl_add_u64 v[232:233], s[68:69], 0, v[164:165]
	s_addc_u32 s29, s69, 0
	s_add_i32 s30, s31, s11
	global_load_lds_dwordx4 v[232:233], off
	v_lshl_add_u64 v[234:235], s[28:29], 0, v[160:161]
	s_mov_b32 m0, s30
	v_lshl_add_u64 v[236:237], s[78:79], 0, v[162:163]
	global_load_lds_dwordx4 v[234:235], off
	v_lshl_add_u64 v[234:235], s[28:29], 0, v[164:165]
	s_add_i32 m0, s30, 0x2000
	s_nop 0
	global_load_lds_dwordx4 v[234:235], off
	v_lshl_add_u64 v[234:235], s[78:79], 0, v[158:159]
	s_mov_b32 m0, s42
	s_nop 0
	global_load_lds_dwordx4 v[234:235], off
	s_mov_b32 m0, s57
	s_nop 0
	global_load_lds_dwordx4 v[236:237], off
	s_waitcnt vmcnt(8)
	s_waitcnt lgkmcnt(0)
	s_barrier
	s_setprio 1
	s_waitcnt lgkmcnt(0)
	v_mfma_f32_16x16x32_bf16 v[62:65], v[130:133], v[176:179], v[62:65]
	v_mfma_f32_16x16x32_bf16 v[46:49], v[130:133], v[188:191], v[46:49]
	v_mfma_f32_16x16x32_bf16 v[30:33], v[130:133], v[196:199], v[30:33]
	v_mfma_f32_16x16x32_bf16 v[14:17], v[130:133], v[204:207], v[14:17]
	v_mfma_f32_16x16x32_bf16 v[10:13], v[138:141], v[204:207], v[10:13]
	v_mfma_f32_16x16x32_bf16 v[26:29], v[138:141], v[196:199], v[26:29]
	v_mfma_f32_16x16x32_bf16 v[42:45], v[138:141], v[188:191], v[42:45]
	v_mfma_f32_16x16x32_bf16 v[58:61], v[138:141], v[176:179], v[58:61]
	v_mfma_f32_16x16x32_bf16 v[58:61], v[142:145], v[180:183], v[58:61]
	v_mfma_f32_16x16x32_bf16 v[42:45], v[142:145], v[192:195], v[42:45]
	v_mfma_f32_16x16x32_bf16 v[26:29], v[142:145], v[200:203], v[26:29]
	v_mfma_f32_16x16x32_bf16 v[10:13], v[142:145], v[208:211], v[10:13]
	v_mfma_f32_16x16x32_bf16 v[14:17], v[134:137], v[208:211], v[14:17]
	v_mfma_f32_16x16x32_bf16 v[30:33], v[134:137], v[200:203], v[30:33]
	v_mfma_f32_16x16x32_bf16 v[46:49], v[134:137], v[192:195], v[46:49]
	v_mfma_f32_16x16x32_bf16 v[62:65], v[134:137], v[180:183], v[62:65]
	s_setprio 0
	s_setprio 1
	v_mfma_f32_16x16x32_bf16 v[54:57], v[146:149], v[176:179], v[54:57]
	v_mfma_f32_16x16x32_bf16 v[38:41], v[146:149], v[188:191], v[38:41]
	v_mfma_f32_16x16x32_bf16 v[22:25], v[146:149], v[196:199], v[22:25]
	v_mfma_f32_16x16x32_bf16 v[6:9], v[146:149], v[204:207], v[6:9]
	v_mfma_f32_16x16x32_bf16 v[2:5], v[154:157], v[204:207], v[2:5]
	v_mfma_f32_16x16x32_bf16 v[18:21], v[154:157], v[196:199], v[18:21]
	v_mfma_f32_16x16x32_bf16 v[34:37], v[154:157], v[188:191], v[34:37]
	v_mfma_f32_16x16x32_bf16 v[50:53], v[154:157], v[176:179], v[50:53]
	v_mfma_f32_16x16x32_bf16 v[50:53], v[172:175], v[180:183], v[50:53]
	v_mfma_f32_16x16x32_bf16 v[34:37], v[172:175], v[192:195], v[34:37]
	v_mfma_f32_16x16x32_bf16 v[18:21], v[172:175], v[200:203], v[18:21]
	v_mfma_f32_16x16x32_bf16 v[2:5], v[172:175], v[208:211], v[2:5]
	v_mfma_f32_16x16x32_bf16 v[6:9], v[150:153], v[208:211], v[6:9]
	v_mfma_f32_16x16x32_bf16 v[22:25], v[150:153], v[200:203], v[22:25]
	v_mfma_f32_16x16x32_bf16 v[38:41], v[150:153], v[192:195], v[38:41]
	v_mfma_f32_16x16x32_bf16 v[54:57], v[150:153], v[180:183], v[54:57]
	s_setprio 0
	s_barrier
	s_add_i32 s30, 0, 0x18000
	s_add_i32 s31, 0, 0x1c000
	v_add_u32_e32 v142, s30, v184
	v_add_u32_e32 v172, s31, v184
	ds_read_b128 v[130:133], v142
	ds_read_b128 v[134:137], v142 offset:1024
	ds_read_b128 v[138:141], v142 offset:2048
	ds_read_b128 v[142:145], v142 offset:3072
	ds_read_b128 v[146:149], v172
	ds_read_b128 v[150:153], v172 offset:1024
	ds_read_b128 v[154:157], v172 offset:2048
	ds_read_b128 v[172:175], v172 offset:3072
	s_add_u32 s28, s78, 0x80000
	s_addc_u32 s29, s79, 0
	s_mov_b32 m0, s67
	v_lshl_add_u64 v[238:239], s[28:29], 0, v[158:159]
	ds_read_b128 v[176:179], v186 offset:32768
	ds_read_b128 v[180:183], v186 offset:33792
	ds_read_b128 v[188:191], v186 offset:34816
	ds_read_b128 v[192:195], v186 offset:35840
	ds_read_b128 v[196:199], v186 offset:36864
	ds_read_b128 v[200:203], v186 offset:37888
	ds_read_b128 v[204:207], v186 offset:38912
	ds_read_b128 v[208:211], v186 offset:39936
	global_load_lds_dwordx4 v[238:239], off
	v_lshl_add_u64 v[238:239], s[28:29], 0, v[162:163]
	s_mov_b32 m0, s72
	s_nop 0
	global_load_lds_dwordx4 v[238:239], off
	s_waitcnt vmcnt(8)
	s_waitcnt lgkmcnt(0)
	s_barrier
	s_setprio 1
	s_waitcnt lgkmcnt(0)
	v_mfma_f32_16x16x32_bf16 v[126:129], v[130:133], v[176:179], v[126:129]
	v_mfma_f32_16x16x32_bf16 v[110:113], v[130:133], v[188:191], v[110:113]
	v_mfma_f32_16x16x32_bf16 v[94:97], v[130:133], v[196:199], v[94:97]
	v_mfma_f32_16x16x32_bf16 v[78:81], v[130:133], v[204:207], v[78:81]
	v_mfma_f32_16x16x32_bf16 v[74:77], v[138:141], v[204:207], v[74:77]
	v_mfma_f32_16x16x32_bf16 v[90:93], v[138:141], v[196:199], v[90:93]
	v_mfma_f32_16x16x32_bf16 v[106:109], v[138:141], v[188:191], v[106:109]
	v_mfma_f32_16x16x32_bf16 v[122:125], v[138:141], v[176:179], v[122:125]
	v_mfma_f32_16x16x32_bf16 v[122:125], v[142:145], v[180:183], v[122:125]
	v_mfma_f32_16x16x32_bf16 v[106:109], v[142:145], v[192:195], v[106:109]
	v_mfma_f32_16x16x32_bf16 v[90:93], v[142:145], v[200:203], v[90:93]
	v_mfma_f32_16x16x32_bf16 v[74:77], v[142:145], v[208:211], v[74:77]
	v_mfma_f32_16x16x32_bf16 v[78:81], v[134:137], v[208:211], v[78:81]
	v_mfma_f32_16x16x32_bf16 v[94:97], v[134:137], v[200:203], v[94:97]
	v_mfma_f32_16x16x32_bf16 v[110:113], v[134:137], v[192:195], v[110:113]
	v_mfma_f32_16x16x32_bf16 v[126:129], v[134:137], v[180:183], v[126:129]
	s_setprio 0
	s_setprio 1
	v_mfma_f32_16x16x32_bf16 v[118:121], v[146:149], v[176:179], v[118:121]
	v_mfma_f32_16x16x32_bf16 v[102:105], v[146:149], v[188:191], v[102:105]
	v_mfma_f32_16x16x32_bf16 v[86:89], v[146:149], v[196:199], v[86:89]
	v_mfma_f32_16x16x32_bf16 v[70:73], v[146:149], v[204:207], v[70:73]
	v_mfma_f32_16x16x32_bf16 v[66:69], v[154:157], v[204:207], v[66:69]
	v_mfma_f32_16x16x32_bf16 v[82:85], v[154:157], v[196:199], v[82:85]
	v_mfma_f32_16x16x32_bf16 v[98:101], v[154:157], v[188:191], v[98:101]
	v_mfma_f32_16x16x32_bf16 v[114:117], v[154:157], v[176:179], v[114:117]
	v_mfma_f32_16x16x32_bf16 v[114:117], v[172:175], v[180:183], v[114:117]
	v_mfma_f32_16x16x32_bf16 v[98:101], v[172:175], v[192:195], v[98:101]
	v_mfma_f32_16x16x32_bf16 v[82:85], v[172:175], v[200:203], v[82:85]
	v_mfma_f32_16x16x32_bf16 v[66:69], v[172:175], v[208:211], v[66:69]
	v_mfma_f32_16x16x32_bf16 v[70:73], v[150:153], v[208:211], v[70:73]
	v_mfma_f32_16x16x32_bf16 v[86:89], v[150:153], v[200:203], v[86:89]
	v_mfma_f32_16x16x32_bf16 v[102:105], v[150:153], v[192:195], v[102:105]
	v_mfma_f32_16x16x32_bf16 v[118:121], v[150:153], v[180:183], v[118:121]
	s_setprio 0
	s_barrier
	s_add_i32 s28, s30, s11
	v_lshl_add_u64 v[212:213], v[212:213], 0, s[62:63]
	s_mov_b32 m0, s28
	ds_read_b128 v[176:179], v186 offset:49152
	ds_read_b128 v[180:183], v186 offset:50176
	ds_read_b128 v[188:191], v186 offset:51200
	ds_read_b128 v[192:195], v186 offset:52224
	ds_read_b128 v[196:199], v186 offset:53248
	ds_read_b128 v[200:203], v186 offset:54272
	ds_read_b128 v[204:207], v186 offset:55296
	ds_read_b128 v[208:211], v186 offset:56320
	global_load_lds_dwordx4 v[212:213], off
	s_add_i32 m0, s28, 0x2000
	s_add_u32 s28, s68, 0x80080
	v_lshl_add_u64 v[212:213], v[232:233], 0, s[62:63]
	s_addc_u32 s29, s69, 0
	s_add_i32 s30, s31, s11
	global_load_lds_dwordx4 v[212:213], off
	v_lshl_add_u64 v[212:213], s[28:29], 0, v[160:161]
	s_mov_b32 m0, s30
	s_nop 0
	global_load_lds_dwordx4 v[212:213], off
	v_lshl_add_u64 v[212:213], s[28:29], 0, v[164:165]
	s_add_i32 m0, s30, 0x2000
	s_nop 0
	global_load_lds_dwordx4 v[212:213], off
	v_lshl_add_u64 v[212:213], v[234:235], 0, s[62:63]
	s_mov_b32 m0, s18
	s_nop 0
	global_load_lds_dwordx4 v[212:213], off
	v_lshl_add_u64 v[212:213], v[236:237], 0, s[62:63]
	s_mov_b32 m0, s19
	s_nop 0
	global_load_lds_dwordx4 v[212:213], off
	s_waitcnt vmcnt(8)
	s_waitcnt lgkmcnt(0)
	s_barrier
	s_setprio 1
	s_waitcnt lgkmcnt(0)
	v_mfma_f32_16x16x32_bf16 v[62:65], v[130:133], v[176:179], v[62:65]
	v_mfma_f32_16x16x32_bf16 v[46:49], v[130:133], v[188:191], v[46:49]
	v_mfma_f32_16x16x32_bf16 v[30:33], v[130:133], v[196:199], v[30:33]
	v_mfma_f32_16x16x32_bf16 v[14:17], v[130:133], v[204:207], v[14:17]
	v_mfma_f32_16x16x32_bf16 v[10:13], v[138:141], v[204:207], v[10:13]
	v_mfma_f32_16x16x32_bf16 v[26:29], v[138:141], v[196:199], v[26:29]
	v_mfma_f32_16x16x32_bf16 v[42:45], v[138:141], v[188:191], v[42:45]
	v_mfma_f32_16x16x32_bf16 v[58:61], v[138:141], v[176:179], v[58:61]
	v_mfma_f32_16x16x32_bf16 v[58:61], v[142:145], v[180:183], v[58:61]
	v_mfma_f32_16x16x32_bf16 v[42:45], v[142:145], v[192:195], v[42:45]
	v_mfma_f32_16x16x32_bf16 v[26:29], v[142:145], v[200:203], v[26:29]
	v_mfma_f32_16x16x32_bf16 v[10:13], v[142:145], v[208:211], v[10:13]
	v_mfma_f32_16x16x32_bf16 v[14:17], v[134:137], v[208:211], v[14:17]
	v_mfma_f32_16x16x32_bf16 v[30:33], v[134:137], v[200:203], v[30:33]
	v_mfma_f32_16x16x32_bf16 v[46:49], v[134:137], v[192:195], v[46:49]
	v_mfma_f32_16x16x32_bf16 v[62:65], v[134:137], v[180:183], v[62:65]
	s_setprio 0
	s_setprio 1
	v_mfma_f32_16x16x32_bf16 v[54:57], v[146:149], v[176:179], v[54:57]
	v_mfma_f32_16x16x32_bf16 v[38:41], v[146:149], v[188:191], v[38:41]
	v_mfma_f32_16x16x32_bf16 v[22:25], v[146:149], v[196:199], v[22:25]
	v_mfma_f32_16x16x32_bf16 v[6:9], v[146:149], v[204:207], v[6:9]
	v_mfma_f32_16x16x32_bf16 v[2:5], v[154:157], v[204:207], v[2:5]
	v_mfma_f32_16x16x32_bf16 v[18:21], v[154:157], v[196:199], v[18:21]
	v_mfma_f32_16x16x32_bf16 v[34:37], v[154:157], v[188:191], v[34:37]
	v_mfma_f32_16x16x32_bf16 v[50:53], v[154:157], v[176:179], v[50:53]
	v_mfma_f32_16x16x32_bf16 v[50:53], v[172:175], v[180:183], v[50:53]
	v_mfma_f32_16x16x32_bf16 v[34:37], v[172:175], v[192:195], v[34:37]
	v_mfma_f32_16x16x32_bf16 v[18:21], v[172:175], v[200:203], v[18:21]
	v_mfma_f32_16x16x32_bf16 v[2:5], v[172:175], v[208:211], v[2:5]
	v_mfma_f32_16x16x32_bf16 v[6:9], v[150:153], v[208:211], v[6:9]
	v_mfma_f32_16x16x32_bf16 v[22:25], v[150:153], v[200:203], v[22:25]
	v_mfma_f32_16x16x32_bf16 v[38:41], v[150:153], v[192:195], v[38:41]
	v_mfma_f32_16x16x32_bf16 v[54:57], v[150:153], v[180:183], v[54:57]
	s_setprio 0
	s_barrier
	s_add_i32 s27, s27, 2
	s_add_u32 s54, s54, 0x100
	s_addc_u32 s55, s55, 0
	s_add_u32 s25, s25, 0x100
	s_addc_u32 s26, s26, 0
	s_cmp_gt_u32 s27, 29
	s_cbranch_scc0 .LBB0_32
	s_and_b64 vcc, exec, s[2:3]
	s_cbranch_vccz .LBB0_35
	s_barrier

.LBB0_132:
	s_add_u32 s23, s48, 0xfff80080
	s_addc_u32 s24, s49, -1
	s_add_i32 s25, 0, 0x10000
	s_cmp_eq_u32 s22, 28
	s_cselect_b32 s69, s3, s24
	s_cselect_b32 s68, s18, s23
	s_cselect_b32 s51, s1, s21
	s_cselect_b32 s50, s19, s20
	s_add_i32 s23, 0, 0x14000
	v_add_u32_e32 v156, s25, v165
	v_add_u32_e32 v169, s23, v165
	ds_read_b128 v[144:147], v156
	ds_read_b128 v[148:151], v156 offset:1024
	ds_read_b128 v[152:155], v156 offset:2048
	ds_read_b128 v[156:159], v156 offset:3072
	ds_read_b128 v[160:163], v169
	ds_read_b128 v[170:173], v169 offset:1024
	ds_read_b128 v[174:177], v169 offset:2048
	ds_read_b128 v[178:181], v169 offset:3072
	v_lshl_add_u64 v[232:233], s[48:49], 0, v[140:141]
	s_add_i32 m0, s45, 0xc000
	ds_read_b128 v[182:185], v168
	ds_read_b128 v[186:189], v168 offset:1024
	ds_read_b128 v[190:193], v168 offset:2048
	ds_read_b128 v[194:197], v168 offset:3072
	ds_read_b128 v[198:201], v168 offset:4096
	ds_read_b128 v[202:205], v168 offset:5120
	ds_read_b128 v[206:209], v168 offset:6144
	ds_read_b128 v[210:213], v168 offset:7168
	global_load_lds_dwordx4 v[232:233], off
	v_lshl_add_u64 v[232:233], s[48:49], 0, v[142:143]
	s_add_i32 m0, s45, 0xe000
	s_nop 0
	global_load_lds_dwordx4 v[232:233], off
	s_waitcnt vmcnt(8)
	s_waitcnt lgkmcnt(0)
	s_barrier
	s_setprio 1
	s_waitcnt lgkmcnt(0)
	v_mfma_f32_16x16x32_bf16 v[126:129], v[144:147], v[182:185], v[126:129]
	v_mfma_f32_16x16x32_bf16 v[110:113], v[144:147], v[190:193], v[110:113]
	v_mfma_f32_16x16x32_bf16 v[102:105], v[144:147], v[198:201], v[102:105]
	v_mfma_f32_16x16x32_bf16 v[86:89], v[144:147], v[206:209], v[86:89]
	v_mfma_f32_16x16x32_bf16 v[78:81], v[152:155], v[206:209], v[78:81]
	v_mfma_f32_16x16x32_bf16 v[94:97], v[152:155], v[198:201], v[94:97]
	v_mfma_f32_16x16x32_bf16 v[106:109], v[152:155], v[190:193], v[106:109]
	v_mfma_f32_16x16x32_bf16 v[122:125], v[152:155], v[182:185], v[122:125]
	v_mfma_f32_16x16x32_bf16 v[122:125], v[156:159], v[186:189], v[122:125]
	v_mfma_f32_16x16x32_bf16 v[106:109], v[156:159], v[194:197], v[106:109]
	v_mfma_f32_16x16x32_bf16 v[94:97], v[156:159], v[202:205], v[94:97]
	v_mfma_f32_16x16x32_bf16 v[78:81], v[156:159], v[210:213], v[78:81]
	v_mfma_f32_16x16x32_bf16 v[86:89], v[148:151], v[210:213], v[86:89]
	v_mfma_f32_16x16x32_bf16 v[102:105], v[148:151], v[202:205], v[102:105]
	v_mfma_f32_16x16x32_bf16 v[110:113], v[148:151], v[194:197], v[110:113]
	v_mfma_f32_16x16x32_bf16 v[126:129], v[148:151], v[186:189], v[126:129]
	s_setprio 0
	s_setprio 1
	v_mfma_f32_16x16x32_bf16 v[118:121], v[160:163], v[182:185], v[118:121]
	v_mfma_f32_16x16x32_bf16 v[98:101], v[160:163], v[190:193], v[98:101]
	v_mfma_f32_16x16x32_bf16 v[82:85], v[160:163], v[198:201], v[82:85]
	v_mfma_f32_16x16x32_bf16 v[70:73], v[160:163], v[206:209], v[70:73]
	v_mfma_f32_16x16x32_bf16 v[66:69], v[174:177], v[206:209], v[66:69]
	v_mfma_f32_16x16x32_bf16 v[74:77], v[174:177], v[198:201], v[74:77]
	v_mfma_f32_16x16x32_bf16 v[90:93], v[174:177], v[190:193], v[90:93]
	v_mfma_f32_16x16x32_bf16 v[114:117], v[174:177], v[182:185], v[114:117]
	v_mfma_f32_16x16x32_bf16 v[114:117], v[178:181], v[186:189], v[114:117]
	v_mfma_f32_16x16x32_bf16 v[90:93], v[178:181], v[194:197], v[90:93]
	v_mfma_f32_16x16x32_bf16 v[74:77], v[178:181], v[202:205], v[74:77]
	v_mfma_f32_16x16x32_bf16 v[66:69], v[178:181], v[210:213], v[66:69]
	v_mfma_f32_16x16x32_bf16 v[70:73], v[170:173], v[210:213], v[70:73]
	v_mfma_f32_16x16x32_bf16 v[82:85], v[170:173], v[202:205], v[82:85]
	v_mfma_f32_16x16x32_bf16 v[98:101], v[170:173], v[194:197], v[98:101]
	v_mfma_f32_16x16x32_bf16 v[118:121], v[170:173], v[186:189], v[118:121]
	s_setprio 0
	s_barrier
	s_add_i32 s24, s25, s16
	v_lshl_add_u64 v[232:233], s[50:51], 0, v[132:133]
	s_mov_b32 m0, s24
	ds_read_b128 v[182:185], v168 offset:16384
	ds_read_b128 v[186:189], v168 offset:17408
	ds_read_b128 v[190:193], v168 offset:18432
	ds_read_b128 v[194:197], v168 offset:19456
	ds_read_b128 v[198:201], v168 offset:20480
	ds_read_b128 v[202:205], v168 offset:21504
	ds_read_b128 v[206:209], v168 offset:22528
	ds_read_b128 v[210:213], v168 offset:23552
	global_load_lds_dwordx4 v[232:233], off
	s_add_i32 m0, s24, 0x2000
	s_add_u32 s24, s50, 0x80000
	v_lshl_add_u64 v[234:235], s[50:51], 0, v[136:137]
	s_addc_u32 s25, s51, 0
	s_add_i32 s23, s23, s16
	global_load_lds_dwordx4 v[234:235], off
	v_lshl_add_u64 v[236:237], s[24:25], 0, v[132:133]
	s_mov_b32 m0, s23
	v_lshl_add_u64 v[238:239], s[68:69], 0, v[134:135]
	global_load_lds_dwordx4 v[236:237], off
	v_lshl_add_u64 v[236:237], s[24:25], 0, v[136:137]
	s_add_i32 m0, s23, 0x2000
	s_nop 0
	global_load_lds_dwordx4 v[236:237], off
	v_lshl_add_u64 v[236:237], s[68:69], 0, v[130:131]
	s_mov_b32 m0, s45
	s_nop 0
	global_load_lds_dwordx4 v[236:237], off
	s_mov_b32 m0, s57
	s_nop 0
	global_load_lds_dwordx4 v[238:239], off
	s_waitcnt vmcnt(8)
	s_waitcnt lgkmcnt(0)
	s_barrier
	s_setprio 1
	s_waitcnt lgkmcnt(0)
	v_mfma_f32_16x16x32_bf16 v[62:65], v[144:147], v[182:185], v[62:65]
	v_mfma_f32_16x16x32_bf16 v[54:57], v[144:147], v[190:193], v[54:57]
	v_mfma_f32_16x16x32_bf16 v[38:41], v[144:147], v[198:201], v[38:41]
	v_mfma_f32_16x16x32_bf16 v[22:25], v[144:147], v[206:209], v[22:25]
	v_mfma_f32_16x16x32_bf16 v[14:17], v[152:155], v[206:209], v[14:17]
	v_mfma_f32_16x16x32_bf16 v[30:33], v[152:155], v[198:201], v[30:33]
	v_mfma_f32_16x16x32_bf16 v[46:49], v[152:155], v[190:193], v[46:49]
	v_mfma_f32_16x16x32_bf16 v[58:61], v[152:155], v[182:185], v[58:61]
	v_mfma_f32_16x16x32_bf16 v[58:61], v[156:159], v[186:189], v[58:61]
	v_mfma_f32_16x16x32_bf16 v[46:49], v[156:159], v[194:197], v[46:49]
	v_mfma_f32_16x16x32_bf16 v[30:33], v[156:159], v[202:205], v[30:33]
	v_mfma_f32_16x16x32_bf16 v[14:17], v[156:159], v[210:213], v[14:17]
	v_mfma_f32_16x16x32_bf16 v[22:25], v[148:151], v[210:213], v[22:25]
	v_mfma_f32_16x16x32_bf16 v[38:41], v[148:151], v[202:205], v[38:41]
	v_mfma_f32_16x16x32_bf16 v[54:57], v[148:151], v[194:197], v[54:57]
	v_mfma_f32_16x16x32_bf16 v[62:65], v[148:151], v[186:189], v[62:65]
	s_setprio 0
	s_setprio 1
	v_mfma_f32_16x16x32_bf16 v[50:53], v[160:163], v[182:185], v[50:53]
	v_mfma_f32_16x16x32_bf16 v[34:37], v[160:163], v[190:193], v[34:37]
	v_mfma_f32_16x16x32_bf16 v[18:21], v[160:163], v[198:201], v[18:21]
	v_mfma_f32_16x16x32_bf16 v[6:9], v[160:163], v[206:209], v[6:9]
	v_mfma_f32_16x16x32_bf16 v[2:5], v[174:177], v[206:209], v[2:5]
	v_mfma_f32_16x16x32_bf16 v[10:13], v[174:177], v[198:201], v[10:13]
	v_mfma_f32_16x16x32_bf16 v[26:29], v[174:177], v[190:193], v[26:29]
	v_mfma_f32_16x16x32_bf16 v[42:45], v[174:177], v[182:185], v[42:45]
	v_mfma_f32_16x16x32_bf16 v[42:45], v[178:181], v[186:189], v[42:45]
	v_mfma_f32_16x16x32_bf16 v[26:29], v[178:181], v[194:197], v[26:29]
	v_mfma_f32_16x16x32_bf16 v[10:13], v[178:181], v[202:205], v[10:13]
	v_mfma_f32_16x16x32_bf16 v[2:5], v[178:181], v[210:213], v[2:5]
	v_mfma_f32_16x16x32_bf16 v[6:9], v[170:173], v[210:213], v[6:9]
	v_mfma_f32_16x16x32_bf16 v[18:21], v[170:173], v[202:205], v[18:21]
	v_mfma_f32_16x16x32_bf16 v[34:37], v[170:173], v[194:197], v[34:37]
	v_mfma_f32_16x16x32_bf16 v[50:53], v[170:173], v[186:189], v[50:53]
	s_setprio 0
	s_barrier
	s_add_i32 s23, 0, 0x18000
	s_add_i32 s26, 0, 0x1c000
	v_add_u32_e32 v156, s23, v165
	v_add_u32_e32 v169, s26, v165
	ds_read_b128 v[144:147], v156
	ds_read_b128 v[148:151], v156 offset:1024
	ds_read_b128 v[152:155], v156 offset:2048
	ds_read_b128 v[156:159], v156 offset:3072
	ds_read_b128 v[160:163], v169
	ds_read_b128 v[170:173], v169 offset:1024
	ds_read_b128 v[174:177], v169 offset:2048
	ds_read_b128 v[178:181], v169 offset:3072
	s_add_u32 s24, s68, 0x80000
	s_addc_u32 s25, s69, 0
	s_mov_b32 m0, s42
	v_lshl_add_u64 v[240:241], s[24:25], 0, v[130:131]
	ds_read_b128 v[182:185], v168 offset:32768
	ds_read_b128 v[186:189], v168 offset:33792
	ds_read_b128 v[190:193], v168 offset:34816
	ds_read_b128 v[194:197], v168 offset:35840
	ds_read_b128 v[198:201], v168 offset:36864
	ds_read_b128 v[202:205], v168 offset:37888
	ds_read_b128 v[206:209], v168 offset:38912
	ds_read_b128 v[210:213], v168 offset:39936
	global_load_lds_dwordx4 v[240:241], off
	v_lshl_add_u64 v[240:241], s[24:25], 0, v[134:135]
	s_mov_b32 m0, s6
	s_nop 0
	global_load_lds_dwordx4 v[240:241], off
	s_waitcnt vmcnt(8)
	s_waitcnt lgkmcnt(0)
	s_barrier
	s_setprio 1
	s_waitcnt lgkmcnt(0)
	v_mfma_f32_16x16x32_bf16 v[126:129], v[144:147], v[182:185], v[126:129]
	v_mfma_f32_16x16x32_bf16 v[110:113], v[144:147], v[190:193], v[110:113]
	v_mfma_f32_16x16x32_bf16 v[102:105], v[144:147], v[198:201], v[102:105]
	v_mfma_f32_16x16x32_bf16 v[86:89], v[144:147], v[206:209], v[86:89]
	v_mfma_f32_16x16x32_bf16 v[78:81], v[152:155], v[206:209], v[78:81]
	v_mfma_f32_16x16x32_bf16 v[94:97], v[152:155], v[198:201], v[94:97]
	v_mfma_f32_16x16x32_bf16 v[106:109], v[152:155], v[190:193], v[106:109]
	v_mfma_f32_16x16x32_bf16 v[122:125], v[152:155], v[182:185], v[122:125]
	v_mfma_f32_16x16x32_bf16 v[122:125], v[156:159], v[186:189], v[122:125]
	v_mfma_f32_16x16x32_bf16 v[106:109], v[156:159], v[194:197], v[106:109]
	v_mfma_f32_16x16x32_bf16 v[94:97], v[156:159], v[202:205], v[94:97]
	v_mfma_f32_16x16x32_bf16 v[78:81], v[156:159], v[210:213], v[78:81]
	v_mfma_f32_16x16x32_bf16 v[86:89], v[148:151], v[210:213], v[86:89]
	v_mfma_f32_16x16x32_bf16 v[102:105], v[148:151], v[202:205], v[102:105]
	v_mfma_f32_16x16x32_bf16 v[110:113], v[148:151], v[194:197], v[110:113]
	v_mfma_f32_16x16x32_bf16 v[126:129], v[148:151], v[186:189], v[126:129]
	s_setprio 0
	s_setprio 1
	v_mfma_f32_16x16x32_bf16 v[118:121], v[160:163], v[182:185], v[118:121]
	v_mfma_f32_16x16x32_bf16 v[98:101], v[160:163], v[190:193], v[98:101]
	v_mfma_f32_16x16x32_bf16 v[82:85], v[160:163], v[198:201], v[82:85]
	v_mfma_f32_16x16x32_bf16 v[70:73], v[160:163], v[206:209], v[70:73]
	v_mfma_f32_16x16x32_bf16 v[66:69], v[174:177], v[206:209], v[66:69]
	v_mfma_f32_16x16x32_bf16 v[74:77], v[174:177], v[198:201], v[74:77]
	v_mfma_f32_16x16x32_bf16 v[90:93], v[174:177], v[190:193], v[90:93]
	v_mfma_f32_16x16x32_bf16 v[114:117], v[174:177], v[182:185], v[114:117]
	v_mfma_f32_16x16x32_bf16 v[114:117], v[178:181], v[186:189], v[114:117]
	v_mfma_f32_16x16x32_bf16 v[90:93], v[178:181], v[194:197], v[90:93]
	v_mfma_f32_16x16x32_bf16 v[74:77], v[178:181], v[202:205], v[74:77]
	v_mfma_f32_16x16x32_bf16 v[66:69], v[178:181], v[210:213], v[66:69]
	v_mfma_f32_16x16x32_bf16 v[70:73], v[170:173], v[210:213], v[70:73]
	v_mfma_f32_16x16x32_bf16 v[82:85], v[170:173], v[202:205], v[82:85]
	v_mfma_f32_16x16x32_bf16 v[98:101], v[170:173], v[194:197], v[98:101]
	v_mfma_f32_16x16x32_bf16 v[118:121], v[170:173], v[186:189], v[118:121]
	s_setprio 0
	s_barrier
	s_add_i32 s23, s23, s16
	v_lshl_add_u64 v[232:233], v[232:233], 0, s[62:63]
	s_mov_b32 m0, s23
	ds_read_b128 v[182:185], v168 offset:49152
	ds_read_b128 v[186:189], v168 offset:50176
	ds_read_b128 v[190:193], v168 offset:51200
	ds_read_b128 v[194:197], v168 offset:52224
	ds_read_b128 v[198:201], v168 offset:53248
	ds_read_b128 v[202:205], v168 offset:54272
	ds_read_b128 v[206:209], v168 offset:55296
	ds_read_b128 v[210:213], v168 offset:56320
	global_load_lds_dwordx4 v[232:233], off
	s_add_i32 m0, s23, 0x2000
	s_add_u32 s24, s50, 0x80080
	v_lshl_add_u64 v[232:233], v[234:235], 0, s[62:63]
	s_addc_u32 s25, s51, 0
	s_add_i32 s23, s26, s16
	global_load_lds_dwordx4 v[232:233], off
	v_lshl_add_u64 v[232:233], s[24:25], 0, v[132:133]
	s_mov_b32 m0, s23
	s_nop 0
	global_load_lds_dwordx4 v[232:233], off
	v_lshl_add_u64 v[232:233], s[24:25], 0, v[136:137]
	s_add_i32 m0, s23, 0x2000
	s_nop 0
	global_load_lds_dwordx4 v[232:233], off
	v_lshl_add_u64 v[232:233], v[236:237], 0, s[62:63]
	s_mov_b32 m0, s76
	s_nop 0
	global_load_lds_dwordx4 v[232:233], off
	v_lshl_add_u64 v[232:233], v[238:239], 0, s[62:63]
	s_mov_b32 m0, s77
	s_nop 0
	global_load_lds_dwordx4 v[232:233], off
	s_waitcnt vmcnt(8)
	s_waitcnt lgkmcnt(0)
	s_barrier
	s_setprio 1
	s_waitcnt lgkmcnt(0)
	v_mfma_f32_16x16x32_bf16 v[62:65], v[144:147], v[182:185], v[62:65]
	v_mfma_f32_16x16x32_bf16 v[54:57], v[144:147], v[190:193], v[54:57]
	v_mfma_f32_16x16x32_bf16 v[38:41], v[144:147], v[198:201], v[38:41]
	v_mfma_f32_16x16x32_bf16 v[22:25], v[144:147], v[206:209], v[22:25]
	v_mfma_f32_16x16x32_bf16 v[14:17], v[152:155], v[206:209], v[14:17]
	v_mfma_f32_16x16x32_bf16 v[30:33], v[152:155], v[198:201], v[30:33]
	v_mfma_f32_16x16x32_bf16 v[46:49], v[152:155], v[190:193], v[46:49]
	v_mfma_f32_16x16x32_bf16 v[58:61], v[152:155], v[182:185], v[58:61]
	v_mfma_f32_16x16x32_bf16 v[58:61], v[156:159], v[186:189], v[58:61]
	v_mfma_f32_16x16x32_bf16 v[46:49], v[156:159], v[194:197], v[46:49]
	v_mfma_f32_16x16x32_bf16 v[30:33], v[156:159], v[202:205], v[30:33]
	v_mfma_f32_16x16x32_bf16 v[14:17], v[156:159], v[210:213], v[14:17]
	v_mfma_f32_16x16x32_bf16 v[22:25], v[148:151], v[210:213], v[22:25]
	v_mfma_f32_16x16x32_bf16 v[38:41], v[148:151], v[202:205], v[38:41]
	v_mfma_f32_16x16x32_bf16 v[54:57], v[148:151], v[194:197], v[54:57]
	v_mfma_f32_16x16x32_bf16 v[62:65], v[148:151], v[186:189], v[62:65]
	s_setprio 0
	s_setprio 1
	v_mfma_f32_16x16x32_bf16 v[50:53], v[160:163], v[182:185], v[50:53]
	v_mfma_f32_16x16x32_bf16 v[34:37], v[160:163], v[190:193], v[34:37]
	v_mfma_f32_16x16x32_bf16 v[18:21], v[160:163], v[198:201], v[18:21]
	v_mfma_f32_16x16x32_bf16 v[6:9], v[160:163], v[206:209], v[6:9]
	v_mfma_f32_16x16x32_bf16 v[2:5], v[174:177], v[206:209], v[2:5]
	v_mfma_f32_16x16x32_bf16 v[10:13], v[174:177], v[198:201], v[10:13]
	v_mfma_f32_16x16x32_bf16 v[26:29], v[174:177], v[190:193], v[26:29]
	v_mfma_f32_16x16x32_bf16 v[42:45], v[174:177], v[182:185], v[42:45]
	v_mfma_f32_16x16x32_bf16 v[42:45], v[178:181], v[186:189], v[42:45]
	v_mfma_f32_16x16x32_bf16 v[26:29], v[178:181], v[194:197], v[26:29]
	v_mfma_f32_16x16x32_bf16 v[10:13], v[178:181], v[202:205], v[10:13]
	v_mfma_f32_16x16x32_bf16 v[2:5], v[178:181], v[210:213], v[2:5]
	v_mfma_f32_16x16x32_bf16 v[6:9], v[170:173], v[210:213], v[6:9]
	v_mfma_f32_16x16x32_bf16 v[18:21], v[170:173], v[202:205], v[18:21]
	v_mfma_f32_16x16x32_bf16 v[34:37], v[170:173], v[194:197], v[34:37]
	v_mfma_f32_16x16x32_bf16 v[50:53], v[170:173], v[186:189], v[50:53]
	s_setprio 0
	s_barrier
	s_add_i32 s22, s22, 2
	s_add_u32 s48, s48, 0x100
	s_addc_u32 s49, s49, 0
	s_add_u32 s20, s20, 0x100
	s_addc_u32 s21, s21, 0
	s_cmp_gt_u32 s22, 29
	s_cbranch_scc0 .LBB0_132
	s_and_b64 vcc, exec, s[10:11]
	s_cbranch_vccz .LBB0_135
	s_barrier

.LBB0_238:
	s_add_u32 s10, s12, 0x100
	s_addc_u32 s11, s13, 0
	s_add_i32 s23, 0, 0x10000
	s_cmpk_eq_i32 s22, 0x52
	s_cselect_b32 vcc_hi, s47, s11
	s_cselect_b32 vcc_lo, s46, s10
	s_cselect_b32 s51, s49, s21
	s_cselect_b32 s50, s48, s20
	s_add_i32 s24, 0, 0x14000
	v_add_u32_e32 v142, s23, v194
	v_add_u32_e32 v158, s24, v194
	ds_read_b128 v[122:125], v142
	ds_read_b128 v[126:129], v142 offset:1024
	ds_read_b128 v[138:141], v142 offset:2048
	ds_read_b128 v[142:145], v142 offset:3072
	ds_read_b128 v[146:149], v158
	ds_read_b128 v[150:153], v158 offset:1024
	ds_read_b128 v[154:157], v158 offset:2048
	ds_read_b128 v[158:161], v158 offset:3072
	v_lshl_add_u64 v[212:213], s[12:13], 0, v[170:171]
	s_add_i32 m0, s57, 0xc000
	ds_read_b128 v[174:177], v198
	ds_read_b128 v[178:181], v198 offset:1024
	ds_read_b128 v[182:185], v198 offset:2048
	ds_read_b128 v[186:189], v198 offset:3072
	ds_read_b128 v[190:193], v198 offset:4096
	ds_read_b128 v[200:203], v198 offset:5120
	ds_read_b128 v[204:207], v198 offset:6144
	ds_read_b128 v[208:211], v198 offset:7168
	global_load_lds_dwordx4 v[212:213], off
	v_lshl_add_u64 v[212:213], s[12:13], 0, v[172:173]
	s_add_i32 m0, s57, 0xe000
	s_nop 0
	global_load_lds_dwordx4 v[212:213], off
	s_waitcnt vmcnt(8)
	s_waitcnt lgkmcnt(0)
	s_barrier
	s_setprio 1
	s_waitcnt lgkmcnt(0)
	v_mfma_f32_16x16x32_bf16 v[134:137], v[122:125], v[174:177], v[134:137]
	v_mfma_f32_16x16x32_bf16 v[110:113], v[122:125], v[182:185], v[110:113]
	v_mfma_f32_16x16x32_bf16 v[94:97], v[122:125], v[190:193], v[94:97]
	v_mfma_f32_16x16x32_bf16 v[78:81], v[122:125], v[204:207], v[78:81]
	v_mfma_f32_16x16x32_bf16 v[74:77], v[138:141], v[204:207], v[74:77]
	v_mfma_f32_16x16x32_bf16 v[90:93], v[138:141], v[190:193], v[90:93]
	v_mfma_f32_16x16x32_bf16 v[106:109], v[138:141], v[182:185], v[106:109]
	v_mfma_f32_16x16x32_bf16 v[130:133], v[138:141], v[174:177], v[130:133]
	v_mfma_f32_16x16x32_bf16 v[130:133], v[142:145], v[178:181], v[130:133]
	v_mfma_f32_16x16x32_bf16 v[106:109], v[142:145], v[186:189], v[106:109]
	v_mfma_f32_16x16x32_bf16 v[90:93], v[142:145], v[200:203], v[90:93]
	v_mfma_f32_16x16x32_bf16 v[74:77], v[142:145], v[208:211], v[74:77]
	v_mfma_f32_16x16x32_bf16 v[78:81], v[126:129], v[208:211], v[78:81]
	v_mfma_f32_16x16x32_bf16 v[94:97], v[126:129], v[200:203], v[94:97]
	v_mfma_f32_16x16x32_bf16 v[110:113], v[126:129], v[186:189], v[110:113]
	v_mfma_f32_16x16x32_bf16 v[134:137], v[126:129], v[178:181], v[134:137]
	s_setprio 0
	s_setprio 1
	v_mfma_f32_16x16x32_bf16 v[118:121], v[146:149], v[174:177], v[118:121]
	v_mfma_f32_16x16x32_bf16 v[102:105], v[146:149], v[182:185], v[102:105]
	v_mfma_f32_16x16x32_bf16 v[86:89], v[146:149], v[190:193], v[86:89]
	v_mfma_f32_16x16x32_bf16 v[70:73], v[146:149], v[204:207], v[70:73]
	v_mfma_f32_16x16x32_bf16 v[66:69], v[154:157], v[204:207], v[66:69]
	v_mfma_f32_16x16x32_bf16 v[82:85], v[154:157], v[190:193], v[82:85]
	v_mfma_f32_16x16x32_bf16 v[98:101], v[154:157], v[182:185], v[98:101]
	v_mfma_f32_16x16x32_bf16 v[114:117], v[154:157], v[174:177], v[114:117]
	v_mfma_f32_16x16x32_bf16 v[114:117], v[158:161], v[178:181], v[114:117]
	v_mfma_f32_16x16x32_bf16 v[98:101], v[158:161], v[186:189], v[98:101]
	v_mfma_f32_16x16x32_bf16 v[82:85], v[158:161], v[200:203], v[82:85]
	v_mfma_f32_16x16x32_bf16 v[66:69], v[158:161], v[208:211], v[66:69]
	v_mfma_f32_16x16x32_bf16 v[70:73], v[150:153], v[208:211], v[70:73]
	v_mfma_f32_16x16x32_bf16 v[86:89], v[150:153], v[200:203], v[86:89]
	v_mfma_f32_16x16x32_bf16 v[102:105], v[150:153], v[186:189], v[102:105]
	v_mfma_f32_16x16x32_bf16 v[118:121], v[150:153], v[178:181], v[118:121]
	s_setprio 0
	s_barrier
	s_add_i32 s12, s23, s42
	v_lshl_add_u64 v[212:213], s[50:51], 0, v[164:165]
	s_mov_b32 m0, s12
	ds_read_b128 v[174:177], v198 offset:16384
	ds_read_b128 v[178:181], v198 offset:17408
	ds_read_b128 v[182:185], v198 offset:18432
	ds_read_b128 v[186:189], v198 offset:19456
	ds_read_b128 v[190:193], v198 offset:20480
	ds_read_b128 v[200:203], v198 offset:21504
	ds_read_b128 v[204:207], v198 offset:22528
	ds_read_b128 v[208:211], v198 offset:23552
	global_load_lds_dwordx4 v[212:213], off
	s_add_i32 m0, s12, 0x2000
	s_add_u32 s12, s50, 0x158000
	v_lshl_add_u64 v[232:233], s[50:51], 0, v[168:169]
	s_addc_u32 s13, s51, 0
	s_add_i32 s23, s24, s42
	global_load_lds_dwordx4 v[232:233], off
	v_lshl_add_u64 v[234:235], s[12:13], 0, v[164:165]
	s_mov_b32 m0, s23
	v_lshl_add_u64 v[236:237], vcc, 0, v[166:167]
	global_load_lds_dwordx4 v[234:235], off
	v_lshl_add_u64 v[234:235], s[12:13], 0, v[168:169]
	s_add_i32 m0, s23, 0x2000
	s_nop 0
	global_load_lds_dwordx4 v[234:235], off
	v_lshl_add_u64 v[234:235], vcc, 0, v[162:163]
	s_mov_b32 m0, s57
	s_nop 0
	global_load_lds_dwordx4 v[234:235], off
	s_mov_b32 m0, s58
	s_nop 0
	global_load_lds_dwordx4 v[236:237], off
	s_waitcnt vmcnt(8)
	s_waitcnt lgkmcnt(0)
	s_barrier
	s_setprio 1
	s_waitcnt lgkmcnt(0)
	v_mfma_f32_16x16x32_bf16 v[62:65], v[122:125], v[174:177], v[62:65]
	v_mfma_f32_16x16x32_bf16 v[46:49], v[122:125], v[182:185], v[46:49]
	v_mfma_f32_16x16x32_bf16 v[30:33], v[122:125], v[190:193], v[30:33]
	v_mfma_f32_16x16x32_bf16 v[14:17], v[122:125], v[204:207], v[14:17]
	v_mfma_f32_16x16x32_bf16 v[10:13], v[138:141], v[204:207], v[10:13]
	v_mfma_f32_16x16x32_bf16 v[26:29], v[138:141], v[190:193], v[26:29]
	v_mfma_f32_16x16x32_bf16 v[42:45], v[138:141], v[182:185], v[42:45]
	v_mfma_f32_16x16x32_bf16 v[58:61], v[138:141], v[174:177], v[58:61]
	v_mfma_f32_16x16x32_bf16 v[58:61], v[142:145], v[178:181], v[58:61]
	v_mfma_f32_16x16x32_bf16 v[42:45], v[142:145], v[186:189], v[42:45]
	v_mfma_f32_16x16x32_bf16 v[26:29], v[142:145], v[200:203], v[26:29]
	v_mfma_f32_16x16x32_bf16 v[10:13], v[142:145], v[208:211], v[10:13]
	v_mfma_f32_16x16x32_bf16 v[14:17], v[126:129], v[208:211], v[14:17]
	v_mfma_f32_16x16x32_bf16 v[30:33], v[126:129], v[200:203], v[30:33]
	v_mfma_f32_16x16x32_bf16 v[46:49], v[126:129], v[186:189], v[46:49]
	v_mfma_f32_16x16x32_bf16 v[62:65], v[126:129], v[178:181], v[62:65]
	s_setprio 0
	s_setprio 1
	v_mfma_f32_16x16x32_bf16 v[54:57], v[146:149], v[174:177], v[54:57]
	v_mfma_f32_16x16x32_bf16 v[38:41], v[146:149], v[182:185], v[38:41]
	v_mfma_f32_16x16x32_bf16 v[22:25], v[146:149], v[190:193], v[22:25]
	v_mfma_f32_16x16x32_bf16 v[6:9], v[146:149], v[204:207], v[6:9]
	v_mfma_f32_16x16x32_bf16 v[2:5], v[154:157], v[204:207], v[2:5]
	v_mfma_f32_16x16x32_bf16 v[18:21], v[154:157], v[190:193], v[18:21]
	v_mfma_f32_16x16x32_bf16 v[34:37], v[154:157], v[182:185], v[34:37]
	v_mfma_f32_16x16x32_bf16 v[50:53], v[154:157], v[174:177], v[50:53]
	v_mfma_f32_16x16x32_bf16 v[50:53], v[158:161], v[178:181], v[50:53]
	v_mfma_f32_16x16x32_bf16 v[34:37], v[158:161], v[186:189], v[34:37]
	v_mfma_f32_16x16x32_bf16 v[18:21], v[158:161], v[200:203], v[18:21]
	v_mfma_f32_16x16x32_bf16 v[2:5], v[158:161], v[208:211], v[2:5]
	v_mfma_f32_16x16x32_bf16 v[6:9], v[150:153], v[208:211], v[6:9]
	v_mfma_f32_16x16x32_bf16 v[22:25], v[150:153], v[200:203], v[22:25]
	v_mfma_f32_16x16x32_bf16 v[38:41], v[150:153], v[186:189], v[38:41]
	v_mfma_f32_16x16x32_bf16 v[54:57], v[150:153], v[178:181], v[54:57]
	s_setprio 0
	s_barrier
	s_add_i32 s23, 0, 0x18000
	s_add_i32 s24, 0, 0x1c000
	v_add_u32_e32 v142, s23, v194
	v_add_u32_e32 v158, s24, v194
	ds_read_b128 v[122:125], v142
	ds_read_b128 v[126:129], v142 offset:1024
	ds_read_b128 v[138:141], v142 offset:2048
	ds_read_b128 v[142:145], v142 offset:3072
	ds_read_b128 v[146:149], v158
	ds_read_b128 v[150:153], v158 offset:1024
	ds_read_b128 v[154:157], v158 offset:2048
	ds_read_b128 v[158:161], v158 offset:3072
	s_add_u32 s12, vcc_lo, 0x158000
	s_addc_u32 s13, vcc_hi, 0
	s_mov_b32 m0, s67
	v_lshl_add_u64 v[238:239], s[12:13], 0, v[162:163]
	ds_read_b128 v[174:177], v198 offset:32768
	ds_read_b128 v[178:181], v198 offset:33792
	ds_read_b128 v[182:185], v198 offset:34816
	ds_read_b128 v[186:189], v198 offset:35840
	ds_read_b128 v[190:193], v198 offset:36864
	ds_read_b128 v[200:203], v198 offset:37888
	ds_read_b128 v[204:207], v198 offset:38912
	ds_read_b128 v[208:211], v198 offset:39936
	global_load_lds_dwordx4 v[238:239], off
	v_lshl_add_u64 v[238:239], s[12:13], 0, v[166:167]
	s_mov_b32 m0, s76
	s_nop 0
	global_load_lds_dwordx4 v[238:239], off
	s_waitcnt vmcnt(8)
	s_waitcnt lgkmcnt(0)
	s_barrier
	s_setprio 1
	s_waitcnt lgkmcnt(0)
	v_mfma_f32_16x16x32_bf16 v[134:137], v[122:125], v[174:177], v[134:137]
	v_mfma_f32_16x16x32_bf16 v[110:113], v[122:125], v[182:185], v[110:113]
	v_mfma_f32_16x16x32_bf16 v[94:97], v[122:125], v[190:193], v[94:97]
	v_mfma_f32_16x16x32_bf16 v[78:81], v[122:125], v[204:207], v[78:81]
	v_mfma_f32_16x16x32_bf16 v[74:77], v[138:141], v[204:207], v[74:77]
	v_mfma_f32_16x16x32_bf16 v[90:93], v[138:141], v[190:193], v[90:93]
	v_mfma_f32_16x16x32_bf16 v[106:109], v[138:141], v[182:185], v[106:109]
	v_mfma_f32_16x16x32_bf16 v[130:133], v[138:141], v[174:177], v[130:133]
	v_mfma_f32_16x16x32_bf16 v[130:133], v[142:145], v[178:181], v[130:133]
	v_mfma_f32_16x16x32_bf16 v[106:109], v[142:145], v[186:189], v[106:109]
	v_mfma_f32_16x16x32_bf16 v[90:93], v[142:145], v[200:203], v[90:93]
	v_mfma_f32_16x16x32_bf16 v[74:77], v[142:145], v[208:211], v[74:77]
	v_mfma_f32_16x16x32_bf16 v[78:81], v[126:129], v[208:211], v[78:81]
	v_mfma_f32_16x16x32_bf16 v[94:97], v[126:129], v[200:203], v[94:97]
	v_mfma_f32_16x16x32_bf16 v[110:113], v[126:129], v[186:189], v[110:113]
	v_mfma_f32_16x16x32_bf16 v[134:137], v[126:129], v[178:181], v[134:137]
	s_setprio 0
	s_setprio 1
	v_mfma_f32_16x16x32_bf16 v[118:121], v[146:149], v[174:177], v[118:121]
	v_mfma_f32_16x16x32_bf16 v[102:105], v[146:149], v[182:185], v[102:105]
	v_mfma_f32_16x16x32_bf16 v[86:89], v[146:149], v[190:193], v[86:89]
	v_mfma_f32_16x16x32_bf16 v[70:73], v[146:149], v[204:207], v[70:73]
	v_mfma_f32_16x16x32_bf16 v[66:69], v[154:157], v[204:207], v[66:69]
	v_mfma_f32_16x16x32_bf16 v[82:85], v[154:157], v[190:193], v[82:85]
	v_mfma_f32_16x16x32_bf16 v[98:101], v[154:157], v[182:185], v[98:101]
	v_mfma_f32_16x16x32_bf16 v[114:117], v[154:157], v[174:177], v[114:117]
	v_mfma_f32_16x16x32_bf16 v[114:117], v[158:161], v[178:181], v[114:117]
	v_mfma_f32_16x16x32_bf16 v[98:101], v[158:161], v[186:189], v[98:101]
	v_mfma_f32_16x16x32_bf16 v[82:85], v[158:161], v[200:203], v[82:85]
	v_mfma_f32_16x16x32_bf16 v[66:69], v[158:161], v[208:211], v[66:69]
	v_mfma_f32_16x16x32_bf16 v[70:73], v[150:153], v[208:211], v[70:73]
	v_mfma_f32_16x16x32_bf16 v[86:89], v[150:153], v[200:203], v[86:89]
	v_mfma_f32_16x16x32_bf16 v[102:105], v[150:153], v[186:189], v[102:105]
	v_mfma_f32_16x16x32_bf16 v[118:121], v[150:153], v[178:181], v[118:121]
	s_setprio 0
	s_barrier
	s_add_i32 s12, s23, s42
	v_lshl_add_u64 v[212:213], v[212:213], 0, s[62:63]
	s_mov_b32 m0, s12
	ds_read_b128 v[174:177], v198 offset:49152
	ds_read_b128 v[178:181], v198 offset:50176
	ds_read_b128 v[182:185], v198 offset:51200
	ds_read_b128 v[186:189], v198 offset:52224
	ds_read_b128 v[190:193], v198 offset:53248
	ds_read_b128 v[200:203], v198 offset:54272
	ds_read_b128 v[204:207], v198 offset:55296
	ds_read_b128 v[208:211], v198 offset:56320
	global_load_lds_dwordx4 v[212:213], off
	s_add_i32 m0, s12, 0x2000
	s_add_u32 s12, s50, 0x158080
	v_lshl_add_u64 v[212:213], v[232:233], 0, s[62:63]
	s_addc_u32 s13, s51, 0
	s_add_i32 s23, s24, s42
	global_load_lds_dwordx4 v[212:213], off
	v_lshl_add_u64 v[212:213], s[12:13], 0, v[164:165]
	s_mov_b32 m0, s23
	s_nop 0
	global_load_lds_dwordx4 v[212:213], off
	v_lshl_add_u64 v[212:213], s[12:13], 0, v[168:169]
	s_add_i32 m0, s23, 0x2000
	s_nop 0
	global_load_lds_dwordx4 v[212:213], off
	v_lshl_add_u64 v[212:213], v[234:235], 0, s[62:63]
	s_mov_b32 m0, s1
	s_nop 0
	global_load_lds_dwordx4 v[212:213], off
	v_lshl_add_u64 v[212:213], v[236:237], 0, s[62:63]
	s_mov_b32 m0, s52
	s_nop 0
	global_load_lds_dwordx4 v[212:213], off
	s_waitcnt vmcnt(8)
	s_waitcnt lgkmcnt(0)
	s_barrier
	s_setprio 1
	s_waitcnt lgkmcnt(0)
	v_mfma_f32_16x16x32_bf16 v[62:65], v[122:125], v[174:177], v[62:65]
	v_mfma_f32_16x16x32_bf16 v[46:49], v[122:125], v[182:185], v[46:49]
	v_mfma_f32_16x16x32_bf16 v[30:33], v[122:125], v[190:193], v[30:33]
	v_mfma_f32_16x16x32_bf16 v[14:17], v[122:125], v[204:207], v[14:17]
	v_mfma_f32_16x16x32_bf16 v[10:13], v[138:141], v[204:207], v[10:13]
	v_mfma_f32_16x16x32_bf16 v[26:29], v[138:141], v[190:193], v[26:29]
	v_mfma_f32_16x16x32_bf16 v[42:45], v[138:141], v[182:185], v[42:45]
	v_mfma_f32_16x16x32_bf16 v[58:61], v[138:141], v[174:177], v[58:61]
	v_mfma_f32_16x16x32_bf16 v[58:61], v[142:145], v[178:181], v[58:61]
	v_mfma_f32_16x16x32_bf16 v[42:45], v[142:145], v[186:189], v[42:45]
	v_mfma_f32_16x16x32_bf16 v[26:29], v[142:145], v[200:203], v[26:29]
	v_mfma_f32_16x16x32_bf16 v[10:13], v[142:145], v[208:211], v[10:13]
	v_mfma_f32_16x16x32_bf16 v[14:17], v[126:129], v[208:211], v[14:17]
	v_mfma_f32_16x16x32_bf16 v[30:33], v[126:129], v[200:203], v[30:33]
	v_mfma_f32_16x16x32_bf16 v[46:49], v[126:129], v[186:189], v[46:49]
	v_mfma_f32_16x16x32_bf16 v[62:65], v[126:129], v[178:181], v[62:65]
	s_setprio 0
	s_setprio 1
	v_mfma_f32_16x16x32_bf16 v[54:57], v[146:149], v[174:177], v[54:57]
	v_mfma_f32_16x16x32_bf16 v[38:41], v[146:149], v[182:185], v[38:41]
	v_mfma_f32_16x16x32_bf16 v[22:25], v[146:149], v[190:193], v[22:25]
	v_mfma_f32_16x16x32_bf16 v[6:9], v[146:149], v[204:207], v[6:9]
	v_mfma_f32_16x16x32_bf16 v[2:5], v[154:157], v[204:207], v[2:5]
	v_mfma_f32_16x16x32_bf16 v[18:21], v[154:157], v[190:193], v[18:21]
	v_mfma_f32_16x16x32_bf16 v[34:37], v[154:157], v[182:185], v[34:37]
	v_mfma_f32_16x16x32_bf16 v[50:53], v[154:157], v[174:177], v[50:53]
	v_mfma_f32_16x16x32_bf16 v[50:53], v[158:161], v[178:181], v[50:53]
	v_mfma_f32_16x16x32_bf16 v[34:37], v[158:161], v[186:189], v[34:37]
	v_mfma_f32_16x16x32_bf16 v[18:21], v[158:161], v[200:203], v[18:21]
	v_mfma_f32_16x16x32_bf16 v[2:5], v[158:161], v[208:211], v[2:5]
	v_mfma_f32_16x16x32_bf16 v[6:9], v[150:153], v[208:211], v[6:9]
	v_mfma_f32_16x16x32_bf16 v[22:25], v[150:153], v[200:203], v[22:25]
	v_mfma_f32_16x16x32_bf16 v[38:41], v[150:153], v[186:189], v[38:41]
	v_mfma_f32_16x16x32_bf16 v[54:57], v[150:153], v[178:181], v[54:57]
	s_setprio 0
	s_barrier
	s_add_i32 s22, s22, 2
	s_add_u32 s20, s20, 0x100
	s_addc_u32 s21, s21, 0
	s_cmpk_gt_u32 s22, 0x53
	s_mov_b64 s[12:13], s[10:11]
	s_cbranch_scc0 .LBB0_238
	s_and_b64 vcc, exec, s[2:3]
	s_cbranch_vccz .LBB0_241
	s_barrier

.LBB0_340:
	s_add_u32 s22, s46, 0xfff80080
	s_addc_u32 s23, s47, -1
	s_add_i32 s24, 0, 0x10000
	s_cmp_eq_u32 s21, 28
	s_cselect_b32 s51, s1, s23
	s_cselect_b32 s50, s13, s22
	v_add_u32_e32 v148, s24, v152
	s_cselect_b32 s49, s11, s20
	s_cselect_b32 s48, s18, s19
	s_add_i32 s25, 0, 0x14000
	ds_read_b128 v[144:147], v148
	ds_read_b128 v[156:159], v148 offset:1024
	ds_read_b128 v[160:163], v148 offset:2048
	ds_read_b128 v[164:167], v148 offset:3072
	v_add_u32_e32 v148, s25, v152
	ds_read_b128 v[168:171], v148
	ds_read_b128 v[172:175], v148 offset:1024
	ds_read_b128 v[176:179], v148 offset:2048
	ds_read_b128 v[180:183], v148 offset:3072
	v_lshl_add_u64 v[148:149], s[46:47], 0, v[140:141]
	s_add_i32 m0, s3, 0xc000
	ds_read_b128 v[184:187], v154
	ds_read_b128 v[188:191], v154 offset:1024
	ds_read_b128 v[192:195], v154 offset:2048
	ds_read_b128 v[196:199], v154 offset:3072
	ds_read_b128 v[200:203], v154 offset:4096
	ds_read_b128 v[204:207], v154 offset:5120
	ds_read_b128 v[208:211], v154 offset:6144
	ds_read_b128 v[232:235], v154 offset:7168
	global_load_lds_dwordx4 v[148:149], off
	v_lshl_add_u64 v[148:149], s[46:47], 0, v[142:143]
	s_add_i32 m0, s3, 0xe000
	s_nop 0
	global_load_lds_dwordx4 v[148:149], off
	s_waitcnt vmcnt(8)
	s_waitcnt lgkmcnt(0)
	s_barrier
	s_setprio 1
	s_waitcnt lgkmcnt(0)
	v_mfma_f32_16x16x32_bf16 v[126:129], v[144:147], v[184:187], v[126:129]
	v_mfma_f32_16x16x32_bf16 v[110:113], v[144:147], v[192:195], v[110:113]
	v_mfma_f32_16x16x32_bf16 v[94:97], v[144:147], v[200:203], v[94:97]
	v_mfma_f32_16x16x32_bf16 v[78:81], v[144:147], v[208:211], v[78:81]
	v_mfma_f32_16x16x32_bf16 v[74:77], v[160:163], v[208:211], v[74:77]
	v_mfma_f32_16x16x32_bf16 v[90:93], v[160:163], v[200:203], v[90:93]
	v_mfma_f32_16x16x32_bf16 v[106:109], v[160:163], v[192:195], v[106:109]
	v_mfma_f32_16x16x32_bf16 v[122:125], v[160:163], v[184:187], v[122:125]
	v_mfma_f32_16x16x32_bf16 v[122:125], v[164:167], v[188:191], v[122:125]
	v_mfma_f32_16x16x32_bf16 v[106:109], v[164:167], v[196:199], v[106:109]
	v_mfma_f32_16x16x32_bf16 v[90:93], v[164:167], v[204:207], v[90:93]
	v_mfma_f32_16x16x32_bf16 v[74:77], v[164:167], v[232:235], v[74:77]
	v_mfma_f32_16x16x32_bf16 v[78:81], v[156:159], v[232:235], v[78:81]
	v_mfma_f32_16x16x32_bf16 v[94:97], v[156:159], v[204:207], v[94:97]
	v_mfma_f32_16x16x32_bf16 v[110:113], v[156:159], v[196:199], v[110:113]
	v_mfma_f32_16x16x32_bf16 v[126:129], v[156:159], v[188:191], v[126:129]
	s_setprio 0
	s_setprio 1
	v_mfma_f32_16x16x32_bf16 v[118:121], v[168:171], v[184:187], v[118:121]
	v_mfma_f32_16x16x32_bf16 v[102:105], v[168:171], v[192:195], v[102:105]
	v_mfma_f32_16x16x32_bf16 v[86:89], v[168:171], v[200:203], v[86:89]
	v_mfma_f32_16x16x32_bf16 v[70:73], v[168:171], v[208:211], v[70:73]
	v_mfma_f32_16x16x32_bf16 v[66:69], v[176:179], v[208:211], v[66:69]
	v_mfma_f32_16x16x32_bf16 v[82:85], v[176:179], v[200:203], v[82:85]
	v_mfma_f32_16x16x32_bf16 v[98:101], v[176:179], v[192:195], v[98:101]
	v_mfma_f32_16x16x32_bf16 v[114:117], v[176:179], v[184:187], v[114:117]
	v_mfma_f32_16x16x32_bf16 v[114:117], v[180:183], v[188:191], v[114:117]
	v_mfma_f32_16x16x32_bf16 v[98:101], v[180:183], v[196:199], v[98:101]
	v_mfma_f32_16x16x32_bf16 v[82:85], v[180:183], v[204:207], v[82:85]
	v_mfma_f32_16x16x32_bf16 v[66:69], v[180:183], v[232:235], v[66:69]
	v_mfma_f32_16x16x32_bf16 v[70:73], v[172:175], v[232:235], v[70:73]
	v_mfma_f32_16x16x32_bf16 v[86:89], v[172:175], v[204:207], v[86:89]
	v_mfma_f32_16x16x32_bf16 v[102:105], v[172:175], v[196:199], v[102:105]
	v_mfma_f32_16x16x32_bf16 v[118:121], v[172:175], v[188:191], v[118:121]
	s_setprio 0
	s_barrier
	s_add_i32 s22, s24, s16
	v_lshl_add_u64 v[148:149], s[48:49], 0, v[134:135]
	s_mov_b32 m0, s22
	ds_read_b128 v[184:187], v154 offset:16384
	ds_read_b128 v[188:191], v154 offset:17408
	ds_read_b128 v[192:195], v154 offset:18432
	ds_read_b128 v[196:199], v154 offset:19456
	ds_read_b128 v[200:203], v154 offset:20480
	ds_read_b128 v[204:207], v154 offset:21504
	ds_read_b128 v[208:211], v154 offset:22528
	ds_read_b128 v[232:235], v154 offset:23552
	global_load_lds_dwordx4 v[148:149], off
	s_add_i32 m0, s22, 0x2000
	s_add_u32 s22, s48, 0x80000
	v_lshl_add_u64 v[212:213], s[48:49], 0, v[130:131]
	s_addc_u32 s23, s49, 0
	s_add_i32 s24, s25, s16
	global_load_lds_dwordx4 v[212:213], off
	v_lshl_add_u64 v[236:237], s[22:23], 0, v[134:135]
	s_mov_b32 m0, s24
	v_lshl_add_u64 v[238:239], s[50:51], 0, v[132:133]
	global_load_lds_dwordx4 v[236:237], off
	v_lshl_add_u64 v[236:237], s[22:23], 0, v[130:131]
	s_add_i32 m0, s24, 0x2000
	s_nop 0
	global_load_lds_dwordx4 v[236:237], off
	v_lshl_add_u64 v[236:237], s[50:51], 0, v[136:137]
	s_mov_b32 m0, s3
	s_nop 0
	global_load_lds_dwordx4 v[236:237], off
	s_mov_b32 m0, s55
	s_nop 0
	global_load_lds_dwordx4 v[238:239], off
	s_waitcnt vmcnt(8)
	s_waitcnt lgkmcnt(0)
	s_barrier
	s_setprio 1
	s_waitcnt lgkmcnt(0)
	v_mfma_f32_16x16x32_bf16 v[62:65], v[144:147], v[184:187], v[62:65]
	v_mfma_f32_16x16x32_bf16 v[46:49], v[144:147], v[192:195], v[46:49]
	v_mfma_f32_16x16x32_bf16 v[30:33], v[144:147], v[200:203], v[30:33]
	v_mfma_f32_16x16x32_bf16 v[14:17], v[144:147], v[208:211], v[14:17]
	v_mfma_f32_16x16x32_bf16 v[10:13], v[160:163], v[208:211], v[10:13]
	v_mfma_f32_16x16x32_bf16 v[26:29], v[160:163], v[200:203], v[26:29]
	v_mfma_f32_16x16x32_bf16 v[42:45], v[160:163], v[192:195], v[42:45]
	v_mfma_f32_16x16x32_bf16 v[58:61], v[160:163], v[184:187], v[58:61]
	v_mfma_f32_16x16x32_bf16 v[58:61], v[164:167], v[188:191], v[58:61]
	v_mfma_f32_16x16x32_bf16 v[42:45], v[164:167], v[196:199], v[42:45]
	v_mfma_f32_16x16x32_bf16 v[26:29], v[164:167], v[204:207], v[26:29]
	v_mfma_f32_16x16x32_bf16 v[10:13], v[164:167], v[232:235], v[10:13]
	v_mfma_f32_16x16x32_bf16 v[14:17], v[156:159], v[232:235], v[14:17]
	v_mfma_f32_16x16x32_bf16 v[30:33], v[156:159], v[204:207], v[30:33]
	v_mfma_f32_16x16x32_bf16 v[46:49], v[156:159], v[196:199], v[46:49]
	v_mfma_f32_16x16x32_bf16 v[62:65], v[156:159], v[188:191], v[62:65]
	s_setprio 0
	s_setprio 1
	v_mfma_f32_16x16x32_bf16 v[54:57], v[168:171], v[184:187], v[54:57]
	v_mfma_f32_16x16x32_bf16 v[38:41], v[168:171], v[192:195], v[38:41]
	v_mfma_f32_16x16x32_bf16 v[22:25], v[168:171], v[200:203], v[22:25]
	v_mfma_f32_16x16x32_bf16 v[6:9], v[168:171], v[208:211], v[6:9]
	v_mfma_f32_16x16x32_bf16 v[2:5], v[176:179], v[208:211], v[2:5]
	v_mfma_f32_16x16x32_bf16 v[18:21], v[176:179], v[200:203], v[18:21]
	v_mfma_f32_16x16x32_bf16 v[34:37], v[176:179], v[192:195], v[34:37]
	v_mfma_f32_16x16x32_bf16 v[50:53], v[176:179], v[184:187], v[50:53]
	v_mfma_f32_16x16x32_bf16 v[50:53], v[180:183], v[188:191], v[50:53]
	v_mfma_f32_16x16x32_bf16 v[34:37], v[180:183], v[196:199], v[34:37]
	v_mfma_f32_16x16x32_bf16 v[18:21], v[180:183], v[204:207], v[18:21]
	v_mfma_f32_16x16x32_bf16 v[2:5], v[180:183], v[232:235], v[2:5]
	v_mfma_f32_16x16x32_bf16 v[6:9], v[172:175], v[232:235], v[6:9]
	v_mfma_f32_16x16x32_bf16 v[22:25], v[172:175], v[204:207], v[22:25]
	v_mfma_f32_16x16x32_bf16 v[38:41], v[172:175], v[196:199], v[38:41]
	v_mfma_f32_16x16x32_bf16 v[54:57], v[172:175], v[188:191], v[54:57]
	s_setprio 0
	s_barrier
	s_add_i32 s24, 0, 0x18000
	v_add_u32_e32 v155, s24, v152
	s_add_i32 s25, 0, 0x1c000
	ds_read_b128 v[144:147], v155
	ds_read_b128 v[156:159], v155 offset:1024
	ds_read_b128 v[160:163], v155 offset:2048
	ds_read_b128 v[164:167], v155 offset:3072
	v_add_u32_e32 v155, s25, v152
	ds_read_b128 v[168:171], v155
	ds_read_b128 v[172:175], v155 offset:1024
	ds_read_b128 v[176:179], v155 offset:2048
	ds_read_b128 v[180:183], v155 offset:3072
	s_add_u32 s22, s50, 0x80000
	s_addc_u32 s23, s51, 0
	s_mov_b32 m0, s57
	v_lshl_add_u64 v[240:241], s[22:23], 0, v[136:137]
	ds_read_b128 v[184:187], v154 offset:32768
	ds_read_b128 v[188:191], v154 offset:33792
	ds_read_b128 v[192:195], v154 offset:34816
	ds_read_b128 v[196:199], v154 offset:35840
	ds_read_b128 v[200:203], v154 offset:36864
	ds_read_b128 v[204:207], v154 offset:37888
	ds_read_b128 v[208:211], v154 offset:38912
	ds_read_b128 v[232:235], v154 offset:39936
	global_load_lds_dwordx4 v[240:241], off
	v_lshl_add_u64 v[240:241], s[22:23], 0, v[132:133]
	s_mov_b32 m0, s68
	s_nop 0
	global_load_lds_dwordx4 v[240:241], off
	s_waitcnt vmcnt(8)
	s_waitcnt lgkmcnt(0)
	s_barrier
	s_setprio 1
	s_waitcnt lgkmcnt(0)
	v_mfma_f32_16x16x32_bf16 v[126:129], v[144:147], v[184:187], v[126:129]
	v_mfma_f32_16x16x32_bf16 v[110:113], v[144:147], v[192:195], v[110:113]
	v_mfma_f32_16x16x32_bf16 v[94:97], v[144:147], v[200:203], v[94:97]
	v_mfma_f32_16x16x32_bf16 v[78:81], v[144:147], v[208:211], v[78:81]
	v_mfma_f32_16x16x32_bf16 v[74:77], v[160:163], v[208:211], v[74:77]
	v_mfma_f32_16x16x32_bf16 v[90:93], v[160:163], v[200:203], v[90:93]
	v_mfma_f32_16x16x32_bf16 v[106:109], v[160:163], v[192:195], v[106:109]
	v_mfma_f32_16x16x32_bf16 v[122:125], v[160:163], v[184:187], v[122:125]
	v_mfma_f32_16x16x32_bf16 v[122:125], v[164:167], v[188:191], v[122:125]
	v_mfma_f32_16x16x32_bf16 v[106:109], v[164:167], v[196:199], v[106:109]
	v_mfma_f32_16x16x32_bf16 v[90:93], v[164:167], v[204:207], v[90:93]
	v_mfma_f32_16x16x32_bf16 v[74:77], v[164:167], v[232:235], v[74:77]
	v_mfma_f32_16x16x32_bf16 v[78:81], v[156:159], v[232:235], v[78:81]
	v_mfma_f32_16x16x32_bf16 v[94:97], v[156:159], v[204:207], v[94:97]
	v_mfma_f32_16x16x32_bf16 v[110:113], v[156:159], v[196:199], v[110:113]
	v_mfma_f32_16x16x32_bf16 v[126:129], v[156:159], v[188:191], v[126:129]
	s_setprio 0
	s_setprio 1
	v_mfma_f32_16x16x32_bf16 v[118:121], v[168:171], v[184:187], v[118:121]
	v_mfma_f32_16x16x32_bf16 v[102:105], v[168:171], v[192:195], v[102:105]
	v_mfma_f32_16x16x32_bf16 v[86:89], v[168:171], v[200:203], v[86:89]
	v_mfma_f32_16x16x32_bf16 v[70:73], v[168:171], v[208:211], v[70:73]
	v_mfma_f32_16x16x32_bf16 v[66:69], v[176:179], v[208:211], v[66:69]
	v_mfma_f32_16x16x32_bf16 v[82:85], v[176:179], v[200:203], v[82:85]
	v_mfma_f32_16x16x32_bf16 v[98:101], v[176:179], v[192:195], v[98:101]
	v_mfma_f32_16x16x32_bf16 v[114:117], v[176:179], v[184:187], v[114:117]
	v_mfma_f32_16x16x32_bf16 v[114:117], v[180:183], v[188:191], v[114:117]
	v_mfma_f32_16x16x32_bf16 v[98:101], v[180:183], v[196:199], v[98:101]
	v_mfma_f32_16x16x32_bf16 v[82:85], v[180:183], v[204:207], v[82:85]
	v_mfma_f32_16x16x32_bf16 v[66:69], v[180:183], v[232:235], v[66:69]
	v_mfma_f32_16x16x32_bf16 v[70:73], v[172:175], v[232:235], v[70:73]
	v_mfma_f32_16x16x32_bf16 v[86:89], v[172:175], v[204:207], v[86:89]
	v_mfma_f32_16x16x32_bf16 v[102:105], v[172:175], v[196:199], v[102:105]
	v_mfma_f32_16x16x32_bf16 v[118:121], v[172:175], v[188:191], v[118:121]
	s_setprio 0
	s_barrier
	s_add_i32 s22, s24, s16
	v_lshl_add_u64 v[148:149], v[148:149], 0, s[62:63]
	s_mov_b32 m0, s22
	ds_read_b128 v[184:187], v154 offset:49152
	ds_read_b128 v[188:191], v154 offset:50176
	ds_read_b128 v[192:195], v154 offset:51200
	ds_read_b128 v[196:199], v154 offset:52224
	ds_read_b128 v[200:203], v154 offset:53248
	ds_read_b128 v[204:207], v154 offset:54272
	ds_read_b128 v[208:211], v154 offset:55296
	ds_read_b128 v[232:235], v154 offset:56320
	global_load_lds_dwordx4 v[148:149], off
	s_add_i32 m0, s22, 0x2000
	s_add_u32 s22, s48, 0x80080
	v_lshl_add_u64 v[148:149], v[212:213], 0, s[62:63]
	s_addc_u32 s23, s49, 0
	s_add_i32 s24, s25, s16
	global_load_lds_dwordx4 v[148:149], off
	v_lshl_add_u64 v[148:149], s[22:23], 0, v[134:135]
	s_mov_b32 m0, s24
	s_nop 0
	global_load_lds_dwordx4 v[148:149], off
	v_lshl_add_u64 v[148:149], s[22:23], 0, v[130:131]
	s_add_i32 m0, s24, 0x2000
	s_nop 0
	global_load_lds_dwordx4 v[148:149], off
	v_lshl_add_u64 v[148:149], v[236:237], 0, s[62:63]
	s_mov_b32 m0, s69
	s_nop 0
	global_load_lds_dwordx4 v[148:149], off
	v_lshl_add_u64 v[148:149], v[238:239], 0, s[62:63]
	s_mov_b32 m0, s70
	s_nop 0
	global_load_lds_dwordx4 v[148:149], off
	s_waitcnt vmcnt(8)
	s_waitcnt lgkmcnt(0)
	s_barrier
	s_setprio 1
	s_waitcnt lgkmcnt(0)
	v_mfma_f32_16x16x32_bf16 v[62:65], v[144:147], v[184:187], v[62:65]
	v_mfma_f32_16x16x32_bf16 v[46:49], v[144:147], v[192:195], v[46:49]
	v_mfma_f32_16x16x32_bf16 v[30:33], v[144:147], v[200:203], v[30:33]
	v_mfma_f32_16x16x32_bf16 v[14:17], v[144:147], v[208:211], v[14:17]
	v_mfma_f32_16x16x32_bf16 v[10:13], v[160:163], v[208:211], v[10:13]
	v_mfma_f32_16x16x32_bf16 v[26:29], v[160:163], v[200:203], v[26:29]
	v_mfma_f32_16x16x32_bf16 v[42:45], v[160:163], v[192:195], v[42:45]
	v_mfma_f32_16x16x32_bf16 v[58:61], v[160:163], v[184:187], v[58:61]
	v_mfma_f32_16x16x32_bf16 v[58:61], v[164:167], v[188:191], v[58:61]
	v_mfma_f32_16x16x32_bf16 v[42:45], v[164:167], v[196:199], v[42:45]
	v_mfma_f32_16x16x32_bf16 v[26:29], v[164:167], v[204:207], v[26:29]
	v_mfma_f32_16x16x32_bf16 v[10:13], v[164:167], v[232:235], v[10:13]
	v_mfma_f32_16x16x32_bf16 v[14:17], v[156:159], v[232:235], v[14:17]
	v_mfma_f32_16x16x32_bf16 v[30:33], v[156:159], v[204:207], v[30:33]
	v_mfma_f32_16x16x32_bf16 v[46:49], v[156:159], v[196:199], v[46:49]
	v_mfma_f32_16x16x32_bf16 v[62:65], v[156:159], v[188:191], v[62:65]
	s_setprio 0
	s_setprio 1
	v_mfma_f32_16x16x32_bf16 v[54:57], v[168:171], v[184:187], v[54:57]
	v_mfma_f32_16x16x32_bf16 v[38:41], v[168:171], v[192:195], v[38:41]
	v_mfma_f32_16x16x32_bf16 v[22:25], v[168:171], v[200:203], v[22:25]
	v_mfma_f32_16x16x32_bf16 v[6:9], v[168:171], v[208:211], v[6:9]
	v_mfma_f32_16x16x32_bf16 v[2:5], v[176:179], v[208:211], v[2:5]
	v_mfma_f32_16x16x32_bf16 v[18:21], v[176:179], v[200:203], v[18:21]
	v_mfma_f32_16x16x32_bf16 v[34:37], v[176:179], v[192:195], v[34:37]
	v_mfma_f32_16x16x32_bf16 v[50:53], v[176:179], v[184:187], v[50:53]
	v_mfma_f32_16x16x32_bf16 v[50:53], v[180:183], v[188:191], v[50:53]
	v_mfma_f32_16x16x32_bf16 v[34:37], v[180:183], v[196:199], v[34:37]
	v_mfma_f32_16x16x32_bf16 v[18:21], v[180:183], v[204:207], v[18:21]
	v_mfma_f32_16x16x32_bf16 v[2:5], v[180:183], v[232:235], v[2:5]
	v_mfma_f32_16x16x32_bf16 v[6:9], v[172:175], v[232:235], v[6:9]
	v_mfma_f32_16x16x32_bf16 v[22:25], v[172:175], v[204:207], v[22:25]
	v_mfma_f32_16x16x32_bf16 v[38:41], v[172:175], v[196:199], v[38:41]
	v_mfma_f32_16x16x32_bf16 v[54:57], v[172:175], v[188:191], v[54:57]
	s_setprio 0
	s_barrier
	s_add_i32 s21, s21, 2
	s_add_u32 s46, s46, 0x100
	s_addc_u32 s47, s47, 0
	s_add_u32 s19, s19, 0x100
	s_addc_u32 s20, s20, 0
	s_cmp_gt_u32 s21, 29
	s_cbranch_scc0 .LBB0_340
	s_and_b64 vcc, exec, s[8:9]
	s_cbranch_vccz .LBB0_343
	s_barrier
